# queue fetch: atomic for next index returns into carry register, wait deferred to end of unit (6 dynamic queues), on top of no-setprio
# speedup vs baseline: 1.0028x; 1.0009x over previous
; __device__ __forceinline__ void p_attn(const Frame& F, KArgs& a, int layer) {
;     ...
;         int u; const int be = bg_split(q, 1636, NBG, u);
;         if (be >= 0) { bg_entry(F, a, 0, layer, be); } else {
;         int su = -1, nu = -1;
;         if (u < 768) su = u; else if (u < 1536) nu = u - 768; else if (u < 1556) su = 768 + (u - 1536); else nu = 768 + (u - 1556);
.LBB0_335:
	v_mov_b32_e32 v227, v0
	s_and_saveexec_b64 s[6:7], s[4:5]
	s_cbranch_execz .LBB0_339
	s_mov_b64 s[10:11], exec
	v_mbcnt_lo_u32_b32 v1, s10, 0
	v_mbcnt_hi_u32_b32 v1, s11, v1
	v_cmp_eq_u32_e32 vcc, 0, v1
	s_and_saveexec_b64 s[8:9], vcc
	s_cbranch_execz .LBB0_338
	s_bcnt1_i32_b64 s10, s[10:11]
	v_mov_b32_e32 v2, s10
	global_atomic_add v227, v0, v2, s[24:25] sc0
.LBB0_338:
	s_or_b64 exec, exec, s[8:9]
.LBB0_339:
	s_or_b64 exec, exec, s[6:7]
	s_lshl_b32 s6, s12, 9
	s_mul_hi_i32 s7, s6, 0x7a0a7ce7
	s_addk_i32 s6, 0x200
	s_lshr_b32 s8, s7, 31
	s_ashr_i32 s7, s7, 10
	s_mul_hi_i32 s6, s6, 0x7a0a7ce7
	s_add_i32 s8, s7, s8
	s_lshr_b32 s7, s6, 31
	s_ashr_i32 s6, s6, 10
	s_add_i32 s6, s6, s7
	s_cmp_gt_i32 s6, s8
	s_cselect_b32 s78, s8, -1
	s_cmp_lt_i32 s78, 0
	s_mov_b64 s[6:7], -1
	s_cbranch_scc0 .LBB0_555
	s_sub_i32 s26, s12, s8
	s_cmpk_lt_i32 s26, 0x300
	s_mov_b32 s11, -1
	s_cbranch_scc1 .LBB0_351
	s_cmpk_gt_u32 s26, 0x5ff
	s_cbranch_scc0 .LBB0_347
	s_cmpk_gt_u32 s26, 0x613
	s_cbranch_scc0 .LBB0_344
	s_add_i32 s11, s26, 0xfffffcec
	s_mov_b64 s[6:7], 0

.LBB0_566:
	s_waitcnt lgkmcnt(0)
	s_barrier
	s_and_saveexec_b64 s[6:7], s[4:5]
	s_cbranch_execz .LBB0_334
	v_mov_b32_e32 v1, s33
	s_waitcnt vmcnt(0)
	ds_write_b32 v1, v227
	s_branch .LBB0_334

; __device__ __forceinline__ void chunk_decode(int cid, int& s, int& c) { if (cid < 66) { s = cid / 33; c = cid - s * 33; } else { const int q = cid - 66; const int s2 = q / 17; s = 2 + s2; c = q - s2 * 17; } }
; __device__ __forceinline__ void p_scanA(const Frame& F, KArgs& a, int layer) {
;     ...
;         int u; const int be = bg_split(q, 808, NBG, u);
;         if (be >= 0) { bg_entry(F, a, 1, layer, be); } else {
;         const bool ssd = u < 404; const int uu = ssd ? u : u - 404; const int cid = uu >> 1, sub = uu & 1;
;         int s, c; chunk_decode(cid, s, c);
.LBB0_618:
	v_mov_b32_e32 v217, v0
	s_and_saveexec_b64 s[6:7], s[4:5]
	s_cbranch_execz .LBB0_622
	s_mov_b64 s[10:11], exec
	v_mbcnt_lo_u32_b32 v1, s10, 0
	v_mbcnt_hi_u32_b32 v1, s11, v1
	v_cmp_eq_u32_e32 vcc, 0, v1
	s_and_saveexec_b64 s[8:9], vcc
	s_cbranch_execz .LBB0_621
	s_bcnt1_i32_b64 s10, s[10:11]
	v_mov_b32_e32 v2, s10
	global_atomic_add v217, v0, v2, s[18:19] sc0
.LBB0_621:
	s_or_b64 exec, exec, s[8:9]
.LBB0_622:
	s_or_b64 exec, exec, s[6:7]
	s_lshl_b32 s6, s12, 7
	s_mul_hi_i32 s7, s6, 0x8c08c08d
	s_add_i32 s7, s7, s6
	s_lshr_b32 s8, s7, 31
	s_ashr_i32 s7, s7, 9
	s_addk_i32 s6, 0x80
	s_add_i32 s8, s7, s8
	s_mul_hi_i32 s7, s6, 0x8c08c08d
	s_add_i32 s7, s7, s6
	s_lshr_b32 s6, s7, 31
	s_ashr_i32 s7, s7, 9
	s_add_i32 s7, s7, s6
	s_cmp_gt_i32 s7, s8
	s_cselect_b32 s24, s8, -1
	s_cmp_lt_i32 s24, 0
	s_mov_b64 s[6:7], -1
	s_cbranch_scc0 .LBB0_714
	s_sub_i32 s8, s12, s8
	s_cmpk_gt_i32 s8, 0x193
	s_cselect_b64 s[6:7], -1, 0
	s_add_i32 s9, s8, 0xfffffe6c
	s_cmpk_lt_i32 s8, 0x194
	s_cselect_b32 s10, s8, s9
	s_ashr_i32 s44, s10, 1
	s_cmpk_gt_i32 s44, 0x41
	s_mov_b64 s[8:9], -1
	s_cbranch_scc0 .LBB0_625
	s_add_i32 s8, s44, 0xffffffbe
	s_mul_hi_u32 s9, s8, 0xf0f0f0f1
	s_lshr_b32 s9, s9, 4
	s_add_i32 s43, s9, 2
	s_mulk_i32 s9, 0xffef
	s_add_i32 s45, s9, s8
	s_mov_b64 s[8:9], 0

.LBB0_723:
	s_waitcnt lgkmcnt(0)
	s_barrier
	s_and_saveexec_b64 s[6:7], s[4:5]
	s_cbranch_execz .LBB0_617
	v_mov_b32_e32 v1, s33
	s_waitcnt vmcnt(0)
	ds_write_b32 v1, v217
	s_branch .LBB0_617

; __device__ __forceinline__ void chunk_decode(int cid, int& s, int& c) { if (cid < 66) { s = cid / 33; c = cid - s * 33; } else { const int q = cid - 66; const int s2 = q / 17; s = 2 + s2; c = q - s2 * 17; } }
; __device__ __forceinline__ void p_scanC(const Frame& F, KArgs& a, int layer) {
;     ...
;         int u; const int be = bg_split(q, 1616, NBG, u);
;         if (be >= 0) { bg_entry(F, a, 2, layer, be); } else {
;         const bool ssd = u < 808; const int uu = ssd ? u : u - 808; const int cid = uu >> 2, sub = uu & 3;
;         int s, c; chunk_decode(cid, s, c);
.LBB0_827:
	v_mov_b32_e32 v209, v32
	s_and_saveexec_b64 s[6:7], s[4:5]
	s_cbranch_execz .LBB0_831
	s_mov_b64 s[10:11], exec
	v_mbcnt_lo_u32_b32 v0, s10, 0
	v_mbcnt_hi_u32_b32 v0, s11, v0
	v_cmp_eq_u32_e32 vcc, 0, v0
	s_and_saveexec_b64 s[8:9], vcc
	s_cbranch_execz .LBB0_830
	s_bcnt1_i32_b64 s10, s[10:11]
	v_mov_b32_e32 v1, s10
	global_atomic_add v209, v32, v1, s[18:19] sc0
.LBB0_830:
	s_or_b64 exec, exec, s[8:9]
.LBB0_831:
	s_or_b64 exec, exec, s[6:7]
	s_mul_i32 s6, s12, 0x348
	s_mul_hi_i32 s7, s6, 0xd578e97d
	s_add_i32 s7, s7, s6
	s_lshr_b32 s8, s7, 31
	s_ashr_i32 s7, s7, 11
	s_addk_i32 s6, 0x348
	s_add_i32 s8, s7, s8
	s_mul_hi_i32 s7, s6, 0xd578e97d
	s_add_i32 s7, s7, s6
	s_lshr_b32 s6, s7, 31
	s_ashr_i32 s7, s7, 11
	s_add_i32 s7, s7, s6
	s_cmp_gt_i32 s7, s8
	s_cselect_b32 s57, s8, -1
	s_cmp_lt_i32 s57, 0
	s_mov_b64 s[6:7], -1
	s_cbranch_scc0 .LBB0_1109
	s_sub_i32 s64, s12, s8
	s_cmpk_gt_i32 s64, 0x327
	s_cselect_b64 s[6:7], -1, 0
	s_add_i32 s8, s64, 0xfffffcd8
	s_cmpk_lt_i32 s64, 0x328
	s_cselect_b32 s10, s64, s8
	s_ashr_i32 s78, s10, 2
	s_cmpk_gt_i32 s78, 0x41
	s_mov_b64 s[8:9], -1
	s_cbranch_scc0 .LBB0_834
	s_add_i32 s8, s78, 0xffffffbe
	s_mul_hi_u32 s9, s8, 0xf0f0f0f1
	s_lshr_b32 s9, s9, 4
	s_add_i32 s65, s9, 2
	s_mulk_i32 s9, 0xffef
	s_add_i32 s66, s9, s8
	s_mov_b64 s[8:9], 0

.LBB0_1135:
	s_waitcnt lgkmcnt(0)
	s_barrier
	s_and_saveexec_b64 s[6:7], s[4:5]
	s_cbranch_execz .LBB0_826
	v_mov_b32_e32 v0, s51
	s_waitcnt vmcnt(0)
	ds_write_b32 v0, v209
	s_branch .LBB0_826

; __device__ __forceinline__ void p_attn(const Frame& F, KArgs& a, int layer) {
;     ...
;         int u; const int be = bg_split(q, 1636, NBG, u);
;         if (be >= 0) { bg_entry(F, a, 0, layer, be); } else {
;         int su = -1, nu = -1;
;         if (u < 768) su = u; else if (u < 1536) nu = u - 768; else if (u < 1556) su = 768 + (u - 1536); else nu = 768 + (u - 1556);
.LBB0_1748:
	v_mov_b32_e32 v227, v0
	s_and_saveexec_b64 s[6:7], s[4:5]
	s_cbranch_execz .LBB0_1752
	s_mov_b64 s[10:11], exec
	v_mbcnt_lo_u32_b32 v1, s10, 0
	v_mbcnt_hi_u32_b32 v1, s11, v1
	v_cmp_eq_u32_e32 vcc, 0, v1
	s_and_saveexec_b64 s[8:9], vcc
	s_cbranch_execz .LBB0_1751
	s_bcnt1_i32_b64 s10, s[10:11]
	v_mov_b32_e32 v2, s10
	global_atomic_add v227, v0, v2, s[20:21] sc0
.LBB0_1751:
	s_or_b64 exec, exec, s[8:9]
.LBB0_1752:
	s_or_b64 exec, exec, s[6:7]
	s_lshl_b32 s6, s12, 9
	s_mul_hi_i32 s7, s6, 0x7a0a7ce7
	s_addk_i32 s6, 0x200
	s_lshr_b32 s8, s7, 31
	s_ashr_i32 s7, s7, 10
	s_mul_hi_i32 s6, s6, 0x7a0a7ce7
	s_add_i32 s8, s7, s8
	s_lshr_b32 s7, s6, 31
	s_ashr_i32 s6, s6, 10
	s_add_i32 s6, s6, s7
	s_cmp_gt_i32 s6, s8
	s_cselect_b32 s78, s8, -1
	s_cmp_lt_i32 s78, 0
	s_mov_b64 s[6:7], -1
	s_cbranch_scc0 .LBB0_1968
	s_sub_i32 s22, s12, s8
	s_cmpk_lt_i32 s22, 0x300
	s_mov_b32 s11, -1
	s_cbranch_scc1 .LBB0_1764
	s_cmpk_gt_u32 s22, 0x5ff
	s_cbranch_scc0 .LBB0_1760
	s_cmpk_gt_u32 s22, 0x613
	s_cbranch_scc0 .LBB0_1757
	s_add_i32 s11, s22, 0xfffffcec
	s_mov_b64 s[6:7], 0

; __device__ __forceinline__ void chunk_decode(int cid, int& s, int& c) { if (cid < 66) { s = cid / 33; c = cid - s * 33; } else { const int q = cid - 66; const int s2 = q / 17; s = 2 + s2; c = q - s2 * 17; } }
; __device__ __forceinline__ void p_scanA(const Frame& F, KArgs& a, int layer) {
;     ...
;         int u; const int be = bg_split(q, 808, NBG, u);
;         if (be >= 0) { bg_entry(F, a, 1, layer, be); } else {
;         const bool ssd = u < 404; const int uu = ssd ? u : u - 404; const int cid = uu >> 1, sub = uu & 1;
;         int s, c; chunk_decode(cid, s, c);
.LBB0_2034:
	s_or_b64 exec, exec, s[8:9]
.LBB0_2035:
	s_or_b64 exec, exec, s[6:7]
	s_lshl_b32 s6, s12, 7
	s_mul_hi_i32 s7, s6, 0x8c08c08d
	s_add_i32 s7, s7, s6
	s_lshr_b32 s8, s7, 31
	s_ashr_i32 s7, s7, 9
	s_addk_i32 s6, 0x80
	s_add_i32 s8, s7, s8
	s_mul_hi_i32 s7, s6, 0x8c08c08d
	s_add_i32 s7, s7, s6
	s_lshr_b32 s6, s7, 31
	s_ashr_i32 s7, s7, 9
	s_add_i32 s7, s7, s6
	s_cmp_gt_i32 s7, s8
	s_cselect_b32 s24, s8, -1
	s_cmp_lt_i32 s24, 0
	s_mov_b64 s[6:7], -1
	s_cbranch_scc0 .LBB0_2127
	s_sub_i32 s8, s12, s8
	s_cmpk_gt_i32 s8, 0x193
	s_cselect_b64 s[6:7], -1, 0
	s_add_i32 s9, s8, 0xfffffe6c
	s_cmpk_lt_i32 s8, 0x194
	s_cselect_b32 s10, s8, s9
	s_ashr_i32 s44, s10, 1
	s_cmpk_gt_i32 s44, 0x41
	s_mov_b64 s[8:9], -1
	s_cbranch_scc0 .LBB0_2038
	s_add_i32 s8, s44, 0xffffffbe
	s_mul_hi_u32 s9, s8, 0xf0f0f0f1
	s_lshr_b32 s9, s9, 4
	s_add_i32 s43, s9, 2
	s_mulk_i32 s9, 0xffef
	s_add_i32 s45, s9, s8
	s_mov_b64 s[8:9], 0

; __device__ __forceinline__ void chunk_decode(int cid, int& s, int& c) { if (cid < 66) { s = cid / 33; c = cid - s * 33; } else { const int q = cid - 66; const int s2 = q / 17; s = 2 + s2; c = q - s2 * 17; } }
; __device__ __forceinline__ void p_scanC(const Frame& F, KArgs& a, int layer) {
;     ...
;         int u; const int be = bg_split(q, 1616, NBG, u);
;         if (be >= 0) { bg_entry(F, a, 2, layer, be); } else {
;         const bool ssd = u < 808; const int uu = ssd ? u : u - 808; const int cid = uu >> 2, sub = uu & 3;
;         int s, c; chunk_decode(cid, s, c);
.LBB0_2243:
	s_or_b64 exec, exec, s[8:9]
.LBB0_2244:
	s_or_b64 exec, exec, s[6:7]
	s_lshl_b32 s6, s12, 9
	s_mul_hi_i32 s7, s6, 0xf6603d99
	s_add_i32 s7, s7, s6
	s_lshr_b32 s8, s7, 31
	s_ashr_i32 s7, s7, 11
	s_addk_i32 s6, 0x200
	s_add_i32 s8, s7, s8
	s_mul_hi_i32 s7, s6, 0xf6603d99
	s_add_i32 s7, s7, s6
	s_lshr_b32 s6, s7, 31
	s_ashr_i32 s7, s7, 11
	s_add_i32 s7, s7, s6
	s_cmp_gt_i32 s7, s8
	s_cselect_b32 s55, s8, -1
	s_cmp_lt_i32 s55, 0
	s_mov_b64 s[6:7], -1
	s_cbranch_scc0 .LBB0_2522
	s_sub_i32 s62, s12, s8
	s_cmpk_gt_i32 s62, 0x327
	s_cselect_b64 s[6:7], -1, 0
	s_add_i32 s8, s62, 0xfffffcd8
	s_cmpk_lt_i32 s62, 0x328
	s_cselect_b32 s10, s62, s8
	s_ashr_i32 s74, s10, 2
	s_cmpk_gt_i32 s74, 0x41
	s_mov_b64 s[8:9], -1
	s_cbranch_scc0 .LBB0_2247
	s_add_i32 s8, s74, 0xffffffbe
	s_mul_hi_u32 s9, s8, 0xf0f0f0f1
	s_lshr_b32 s9, s9, 4
	s_add_i32 s63, s9, 2
	s_mulk_i32 s9, 0xffef
	s_add_i32 s64, s9, s8
	s_mov_b64 s[8:9], 0

.LBB0_2548:
	s_barrier
	s_and_saveexec_b64 s[6:7], s[4:5]
	s_cbranch_execz .LBB0_2239
	v_mov_b32_e32 v0, s49
	s_waitcnt vmcnt(0)
	ds_write_b32 v0, v209
	s_branch .LBB0_2239
